# sample conv unit: 21 chained cache-row loads hoisted into one burst with fresh registers and counted waits (on top of barrier edits)
# baseline (speedup 1.0000x reference)
.LBB0_639:
	v_readlane_b32 s0, v239, 41
	v_readlane_b32 s2, v239, 42
	v_mov_b32_e32 v122, v0
	v_mov_b32_e32 v2, s0
	ds_read2_b64 v[2:5], v2 offset1:1
	s_mov_b32 s83, 0x15000
	s_mov_b32 s90, 0x17000
	s_mov_b32 s48, 0x18000
	s_mov_b32 s52, 0x19000
	s_waitcnt lgkmcnt(0)
	v_readfirstlane_b32 s0, v2
	v_mov_b32_e32 v2, s2
	v_readfirstlane_b32 s1, v3
	v_readfirstlane_b32 s35, v5
	v_readfirstlane_b32 s46, v4
	ds_read2_b64 v[2:5], v2 offset1:1
	v_readlane_b32 s2, v239, 43
	s_add_u32 s0, s0, s21
	s_addc_u32 s1, s1, s20
	s_ashr_i32 s18, s28, 31
	s_waitcnt lgkmcnt(0)
	v_readfirstlane_b32 s34, v2
	v_mov_b32_e32 v2, s2
	v_readfirstlane_b32 s19, v3
	ds_read_b64 v[2:3], v2
	s_movk_i32 s2, 0x5000
	v_lshlrev_b32_e32 v32, 1, v122
	v_ashrrev_i32_e32 v33, 31, v32
	s_waitcnt lgkmcnt(0)
	v_readfirstlane_b32 s15, v3
	v_readfirstlane_b32 s14, v2
	v_lshlrev_b64 v[2:3], 2, v[32:33]
	v_lshl_add_u64 v[56:57], s[0:1], 0, v[2:3]
	v_lshl_add_u64 v[6:7], s[14:15], 0, v[2:3]
	v_lshl_add_u64 v[34:35], v[6:7], 0, s[10:11]
	v_add_co_u32_e32 v6, vcc, s3, v34
	s_lshl_b64 s[0:1], s[38:39], 2
	s_nop 0
	v_addc_co_u32_e32 v7, vcc, 0, v35, vcc
	s_waitcnt vmcnt(0)
	flat_load_dwordx2 v[58:59], v[6:7]
	flat_load_dwordx2 v[60:61], v[56:57]
	v_add_co_u32_e32 v6, vcc, s17, v56
	s_add_u32 s46, s46, s0
	s_nop 0
	v_addc_co_u32_e32 v7, vcc, 0, v57, vcc
	flat_load_dwordx2 v[62:63], v[6:7]
	v_add_co_u32_e32 v6, vcc, s5, v56
	s_addc_u32 s47, s35, s1
	s_nop 0
	v_addc_co_u32_e32 v7, vcc, 0, v57, vcc
	flat_load_dwordx2 v[64:65], v[6:7]
	v_add_co_u32_e32 v6, vcc, s87, v56
	v_readfirstlane_b32 s23, v5
	s_nop 0
	v_addc_co_u32_e32 v7, vcc, 0, v57, vcc
	flat_load_dwordx2 v[66:67], v[6:7]
	v_add_co_u32_e32 v6, vcc, s6, v56
	v_readfirstlane_b32 s22, v4
	s_nop 0
	v_addc_co_u32_e32 v7, vcc, 0, v57, vcc
	flat_load_dwordx2 v[68:69], v[6:7]
	v_add_co_u32_e32 v6, vcc, s2, v56
	v_lshl_add_u64 v[4:5], s[46:47], 0, v[2:3]
	s_nop 0
	v_addc_co_u32_e32 v7, vcc, 0, v57, vcc
	flat_load_dwordx2 v[70:71], v[6:7]
	v_add_co_u32_e32 v6, vcc, s7, v56
	s_mov_b32 s49, 0x1a000
	s_nop 0
	v_addc_co_u32_e32 v7, vcc, 0, v57, vcc
	flat_load_dwordx2 v[72:73], v[6:7]
	v_add_co_u32_e32 v6, vcc, s16, v56
	s_mov_b32 s88, 0x1b000
	s_nop 0
	v_addc_co_u32_e32 v7, vcc, 0, v57, vcc
	flat_load_dwordx2 v[74:75], v[6:7]
	v_add_co_u32_e32 v6, vcc, s3, v56
	s_mov_b32 s3, 0x16000
	s_nop 0
	v_addc_co_u32_e32 v7, vcc, 0, v57, vcc
	flat_load_dwordx2 v[76:77], v[6:7]
	flat_load_dwordx2 v[78:79], v[4:5]
	s_nop 0
	flat_load_dwordx2 v[4:5], v[34:35]
	v_add_co_u32_e32 v6, vcc, s17, v34
	s_mov_b32 s50, 0x1c000
	s_nop 0
	v_addc_co_u32_e32 v7, vcc, 0, v35, vcc
	flat_load_dwordx2 v[92:93], v[6:7]
	v_add_co_u32_e32 v6, vcc, s5, v34
	s_mov_b32 s89, 0x1d000
	s_nop 0
	v_addc_co_u32_e32 v7, vcc, 0, v35, vcc
	flat_load_dwordx2 v[90:91], v[6:7]
	v_add_co_u32_e32 v6, vcc, s87, v34
	s_mov_b32 s35, 0x1e000
	s_nop 0
	v_addc_co_u32_e32 v7, vcc, 0, v35, vcc
	flat_load_dwordx2 v[88:89], v[6:7]
	v_add_co_u32_e32 v6, vcc, s6, v34
	s_mov_b32 s47, 0x14000
	s_nop 0
	v_addc_co_u32_e32 v7, vcc, 0, v35, vcc
	flat_load_dwordx2 v[86:87], v[6:7]
	v_add_co_u32_e32 v6, vcc, s2, v34
	s_mov_b32 s2, 0xa000
	s_nop 0
	v_addc_co_u32_e32 v7, vcc, 0, v35, vcc
	flat_load_dwordx2 v[84:85], v[6:7]
	v_add_co_u32_e32 v6, vcc, s7, v34
	s_mov_b32 s58, 0xb000
	s_nop 0
	v_addc_co_u32_e32 v7, vcc, 0, v35, vcc
	flat_load_dwordx2 v[82:83], v[6:7]
	v_add_co_u32_e32 v6, vcc, s16, v34
	s_mov_b32 s8, 0xc000
	s_nop 0
	v_addc_co_u32_e32 v7, vcc, 0, v35, vcc
	flat_load_dwordx2 v[80:81], v[6:7]
	s_mov_b32 s59, 0xd000
	s_mov_b32 s51, 0xe000
	s_mov_b32 s60, 0xf000
	s_mov_b32 s27, 0x10000
	s_mov_b32 s61, 0x11000
	s_mov_b32 s46, 0x12000
	s_mov_b32 s82, 0x13000
	s_add_u32 s14, s76, s10
	s_mov_b32 s53, 0x9000
	s_addc_u32 s15, s77, s11
	v_lshl_add_u64 v[2:3], s[14:15], 0, v[2:3]
	s_mul_i32 s14, s28, 0x7000
	s_mul_hi_i32 s15, s28, 0x7000
	s_add_u32 s14, s92, s14
	s_addc_u32 s15, s93, s15
	v_lshl_add_u64 v[32:33], v[32:33], 1, s[14:15]
	s_mov_b32 s14, 0xe002000
	s_mov_b32 s97, 0x10000
	s_waitcnt vmcnt(0) lgkmcnt(0)
	v_pk_fma_f32 v[4:5], v[60:61], v[4:5], v[78:79]
	s_nop 0
	v_pk_fma_f32 v[4:5], v[62:63], v[92:93], v[4:5]
	v_pk_fma_f32 v[92:93], v[60:61], v[92:93], v[78:79]
	v_pk_fma_f32 v[4:5], v[64:65], v[90:91], v[4:5]
	v_pk_fma_f32 v[92:93], v[62:63], v[90:91], v[92:93]
	v_pk_fma_f32 v[90:91], v[60:61], v[90:91], v[78:79]
	v_pk_fma_f32 v[4:5], v[66:67], v[88:89], v[4:5]
	v_pk_fma_f32 v[92:93], v[64:65], v[88:89], v[92:93]
	v_pk_fma_f32 v[90:91], v[62:63], v[88:89], v[90:91]
	v_pk_fma_f32 v[88:89], v[60:61], v[88:89], v[78:79]
	v_pk_fma_f32 v[4:5], v[68:69], v[86:87], v[4:5]
	v_pk_fma_f32 v[92:93], v[66:67], v[86:87], v[92:93]
	v_pk_fma_f32 v[88:89], v[62:63], v[86:87], v[88:89]
	v_pk_fma_f32 v[90:91], v[64:65], v[86:87], v[90:91]
	v_pk_fma_f32 v[86:87], v[60:61], v[86:87], v[78:79]
	v_pk_fma_f32 v[4:5], v[70:71], v[84:85], v[4:5]
	v_pk_fma_f32 v[92:93], v[68:69], v[84:85], v[92:93]
	v_pk_fma_f32 v[88:89], v[64:65], v[84:85], v[88:89]
	v_pk_fma_f32 v[90:91], v[66:67], v[84:85], v[90:91]
	v_pk_fma_f32 v[86:87], v[62:63], v[84:85], v[86:87]
	v_pk_fma_f32 v[84:85], v[60:61], v[84:85], v[78:79]
	v_pk_fma_f32 v[4:5], v[72:73], v[82:83], v[4:5]
	v_pk_fma_f32 v[92:93], v[70:71], v[82:83], v[92:93]
	v_pk_fma_f32 v[88:89], v[66:67], v[82:83], v[88:89]
	v_pk_fma_f32 v[84:85], v[62:63], v[82:83], v[84:85]
	v_pk_fma_f32 v[90:91], v[68:69], v[82:83], v[90:91]
	v_pk_fma_f32 v[86:87], v[64:65], v[82:83], v[86:87]
	v_pk_fma_f32 v[4:5], v[74:75], v[80:81], v[4:5]
	v_pk_fma_f32 v[92:93], v[72:73], v[80:81], v[92:93]
	v_pk_fma_f32 v[96:97], v[76:77], v[58:59], v[4:5]
	v_add_co_u32_e32 v4, vcc, s83, v56
	v_pk_fma_f32 v[92:93], v[74:75], v[58:59], v[92:93]
	s_nop 0
	v_addc_co_u32_e32 v5, vcc, 0, v57, vcc
	v_add_co_u32_e32 v6, vcc, s3, v56
	flat_load_dwordx2 v[4:5], v[4:5]
	s_nop 0
	v_addc_co_u32_e32 v7, vcc, 0, v57, vcc
	v_add_co_u32_e32 v8, vcc, s90, v56
	flat_load_dwordx2 v[6:7], v[6:7]
	s_nop 0
	v_addc_co_u32_e32 v9, vcc, 0, v57, vcc
	v_add_co_u32_e32 v10, vcc, s48, v56
	flat_load_dwordx2 v[8:9], v[8:9]
	s_nop 0
	v_addc_co_u32_e32 v11, vcc, 0, v57, vcc
	v_add_co_u32_e32 v12, vcc, s52, v56
	flat_load_dwordx2 v[10:11], v[10:11]
	s_nop 0
	v_addc_co_u32_e32 v13, vcc, 0, v57, vcc
	v_add_co_u32_e32 v14, vcc, s49, v56
	flat_load_dwordx2 v[12:13], v[12:13]
	s_nop 0
	v_addc_co_u32_e32 v15, vcc, 0, v57, vcc
	v_add_co_u32_e32 v16, vcc, s88, v56
	flat_load_dwordx2 v[14:15], v[14:15]
	s_nop 0
	v_addc_co_u32_e32 v17, vcc, 0, v57, vcc
	v_add_co_u32_e32 v24, vcc, s50, v56
	flat_load_dwordx2 v[16:17], v[16:17]
	s_nop 0
	v_addc_co_u32_e32 v25, vcc, 0, v57, vcc
	v_add_co_u32_e32 v26, vcc, s89, v56
	flat_load_dwordx2 v[24:25], v[24:25]
	s_nop 0
	v_addc_co_u32_e32 v27, vcc, 0, v57, vcc
	v_add_co_u32_e32 v28, vcc, s35, v56
	s_mov_b32 s35, 0x16261000
	s_nop 0
	v_addc_co_u32_e32 v29, vcc, 0, v57, vcc
	v_add_co_u32_e32 v30, vcc, s47, v56
	flat_load_dwordx2 v[26:27], v[26:27]
	s_nop 0
	v_addc_co_u32_e32 v31, vcc, 0, v57, vcc
	v_add_co_u32_e32 v36, vcc, s2, v56
	flat_load_dwordx2 v[28:29], v[28:29]
	s_nop 0
	v_addc_co_u32_e32 v37, vcc, 0, v57, vcc
	v_add_co_u32_e32 v38, vcc, s58, v56
	flat_load_dwordx2 v[30:31], v[30:31]
	s_nop 0
	v_addc_co_u32_e32 v39, vcc, 0, v57, vcc
	v_add_co_u32_e32 v40, vcc, s8, v56
	flat_load_dwordx2 v[36:37], v[36:37]
	s_nop 0
	v_addc_co_u32_e32 v41, vcc, 0, v57, vcc
	v_add_co_u32_e32 v42, vcc, s59, v56
	flat_load_dwordx2 v[38:39], v[38:39]
	s_nop 0
	v_addc_co_u32_e32 v43, vcc, 0, v57, vcc
	v_add_co_u32_e32 v44, vcc, s51, v56
	flat_load_dwordx2 v[40:41], v[40:41]
	s_nop 0
	v_addc_co_u32_e32 v45, vcc, 0, v57, vcc
	v_add_co_u32_e32 v46, vcc, s60, v56
	flat_load_dwordx2 v[42:43], v[42:43]
	s_nop 0
	v_addc_co_u32_e32 v47, vcc, 0, v57, vcc
	v_add_co_u32_e32 v48, vcc, s27, v56
	flat_load_dwordx2 v[44:45], v[44:45]
	s_nop 0
	v_addc_co_u32_e32 v49, vcc, 0, v57, vcc
	v_add_co_u32_e32 v50, vcc, s61, v56
	flat_load_dwordx2 v[46:47], v[46:47]
	s_nop 0
	v_addc_co_u32_e32 v51, vcc, 0, v57, vcc
	v_add_co_u32_e32 v52, vcc, s46, v56
	flat_load_dwordx2 v[48:49], v[48:49]
	s_nop 0
	v_addc_co_u32_e32 v53, vcc, 0, v57, vcc
	v_add_co_u32_e32 v54, vcc, s82, v56
	flat_load_dwordx2 v[50:51], v[50:51]
	s_nop 0
	v_addc_co_u32_e32 v55, vcc, 0, v57, vcc
	v_add_co_u32_e32 v56, vcc, s53, v56
	flat_load_dwordx2 v[52:53], v[52:53]
	s_nop 0
	v_addc_co_u32_e32 v57, vcc, 0, v57, vcc
	v_add_co_u32_e32 v102, vcc, s35, v2
	flat_load_dwordx2 v[54:55], v[54:55]
	s_nop 0
	v_addc_co_u32_e32 v103, vcc, 0, v3, vcc
	v_add_co_u32_e32 v94, vcc, s53, v34
	flat_load_dwordx2 v[56:57], v[56:57]
	s_nop 0
	v_addc_co_u32_e32 v95, vcc, 0, v35, vcc
	global_store_dwordx2 v[102:103], v[58:59], off offset:-4096
	v_add_co_u32_e32 v204, vcc, 0x9000, v34
	s_nop 1
	v_addc_co_u32_e32 v205, vcc, 0, v35, vcc
	global_load_dwordx2 v[146:147], v[204:205], off
	v_add_co_u32_e32 v204, vcc, 0xa000, v34
	s_nop 1
	v_addc_co_u32_e32 v205, vcc, 0, v35, vcc
	global_load_dwordx2 v[148:149], v[204:205], off
	v_add_co_u32_e32 v204, vcc, 0xb000, v34
	s_nop 1
	v_addc_co_u32_e32 v205, vcc, 0, v35, vcc
	global_load_dwordx2 v[150:151], v[204:205], off
	v_add_co_u32_e32 v204, vcc, 0xc000, v34
	s_nop 1
	v_addc_co_u32_e32 v205, vcc, 0, v35, vcc
	global_load_dwordx2 v[152:153], v[204:205], off
	v_add_co_u32_e32 v204, vcc, 0xd000, v34
	s_nop 1
	v_addc_co_u32_e32 v205, vcc, 0, v35, vcc
	global_load_dwordx2 v[154:155], v[204:205], off
	v_add_co_u32_e32 v204, vcc, 0xe000, v34
	s_nop 1
	v_addc_co_u32_e32 v205, vcc, 0, v35, vcc
	global_load_dwordx2 v[156:157], v[204:205], off
	v_add_co_u32_e32 v204, vcc, 0xf000, v34
	s_nop 1
	v_addc_co_u32_e32 v205, vcc, 0, v35, vcc
	global_load_dwordx2 v[158:159], v[204:205], off
	v_add_co_u32_e32 v204, vcc, 0x10000, v34
	s_nop 1
	v_addc_co_u32_e32 v205, vcc, 0, v35, vcc
	global_load_dwordx2 v[160:161], v[204:205], off
	v_add_co_u32_e32 v204, vcc, 0x11000, v34
	s_nop 1
	v_addc_co_u32_e32 v205, vcc, 0, v35, vcc
	global_load_dwordx2 v[162:163], v[204:205], off
	v_add_co_u32_e32 v204, vcc, 0x12000, v34
	s_nop 1
	v_addc_co_u32_e32 v205, vcc, 0, v35, vcc
	global_load_dwordx2 v[164:165], v[204:205], off
	v_add_co_u32_e32 v204, vcc, 0x13000, v34
	s_nop 1
	v_addc_co_u32_e32 v205, vcc, 0, v35, vcc
	global_load_dwordx2 v[166:167], v[204:205], off
	v_add_co_u32_e32 v204, vcc, 0x14000, v34
	s_nop 1
	v_addc_co_u32_e32 v205, vcc, 0, v35, vcc
	global_load_dwordx2 v[168:169], v[204:205], off
	v_add_co_u32_e32 v204, vcc, 0x15000, v34
	s_nop 1
	v_addc_co_u32_e32 v205, vcc, 0, v35, vcc
	global_load_dwordx2 v[178:179], v[204:205], off
	v_add_co_u32_e32 v204, vcc, 0x16000, v34
	s_nop 1
	v_addc_co_u32_e32 v205, vcc, 0, v35, vcc
	global_load_dwordx2 v[180:181], v[204:205], off
	v_add_co_u32_e32 v204, vcc, 0x17000, v34
	s_nop 1
	v_addc_co_u32_e32 v205, vcc, 0, v35, vcc
	global_load_dwordx2 v[182:183], v[204:205], off
	v_add_co_u32_e32 v204, vcc, 0x18000, v34
	s_nop 1
	v_addc_co_u32_e32 v205, vcc, 0, v35, vcc
	global_load_dwordx2 v[184:185], v[204:205], off
	v_add_co_u32_e32 v204, vcc, 0x19000, v34
	s_nop 1
	v_addc_co_u32_e32 v205, vcc, 0, v35, vcc
	global_load_dwordx2 v[186:187], v[204:205], off
	v_add_co_u32_e32 v204, vcc, 0x1a000, v34
	s_nop 1
	v_addc_co_u32_e32 v205, vcc, 0, v35, vcc
	global_load_dwordx2 v[188:189], v[204:205], off
	v_add_co_u32_e32 v204, vcc, 0x1b000, v34
	s_nop 1
	v_addc_co_u32_e32 v205, vcc, 0, v35, vcc
	global_load_dwordx2 v[190:191], v[204:205], off
	v_add_co_u32_e32 v204, vcc, 0x1c000, v34
	s_nop 1
	v_addc_co_u32_e32 v205, vcc, 0, v35, vcc
	global_load_dwordx2 v[192:193], v[204:205], off
	v_add_co_u32_e32 v204, vcc, 0x1d000, v34
	s_nop 1
	v_addc_co_u32_e32 v205, vcc, 0, v35, vcc
	global_load_dwordx2 v[194:195], v[204:205], off
	s_nop 0
	s_mov_b32 s35, 0x16263000
	v_pk_fma_f32 v[88:89], v[68:69], v[80:81], v[88:89]
	v_pk_fma_f32 v[84:85], v[64:65], v[80:81], v[84:85]
	v_pk_fma_f32 v[88:89], v[70:71], v[58:59], v[88:89]
	v_pk_fma_f32 v[84:85], v[66:67], v[58:59], v[84:85]
	v_pk_fma_f32 v[82:83], v[60:61], v[82:83], v[78:79]
	v_pk_fma_f32 v[90:91], v[70:71], v[80:81], v[90:91]
	v_pk_fma_f32 v[86:87], v[66:67], v[80:81], v[86:87]
	v_pk_fma_f32 v[82:83], v[62:63], v[80:81], v[82:83]
	v_pk_fma_f32 v[60:61], v[60:61], v[80:81], v[78:79]
	v_pk_fma_f32 v[90:91], v[72:73], v[58:59], v[90:91]
	v_pk_fma_f32 v[86:87], v[68:69], v[58:59], v[86:87]
	v_pk_fma_f32 v[82:83], v[64:65], v[58:59], v[82:83]
	v_pk_fma_f32 v[58:59], v[62:63], v[58:59], v[60:61]
	s_waitcnt vmcnt(20) lgkmcnt(0)
	global_store_dwordx2 v[102:103], v[146:147], off
	v_pk_fma_f32 v[102:103], v[76:77], v[146:147], v[92:93]
	v_add_co_u32_e32 v92, vcc, s2, v34
	v_pk_fma_f32 v[88:89], v[72:73], v[146:147], v[88:89]
	s_nop 0
	v_addc_co_u32_e32 v93, vcc, 0, v35, vcc
	s_nop 0
	v_add_co_u32_e32 v92, vcc, s35, v2
	s_mov_b32 s35, 0x16265000
	s_nop 0
	v_addc_co_u32_e32 v93, vcc, 0, v3, vcc
	v_add_co_u32_e32 v104, vcc, s58, v34
	v_pk_fma_f32 v[84:85], v[68:69], v[146:147], v[84:85]
	s_nop 0
	v_addc_co_u32_e32 v105, vcc, 0, v35, vcc
	v_pk_fma_f32 v[96:97], v[56:57], v[146:147], v[96:97]
	v_pk_fma_f32 v[58:59], v[64:65], v[146:147], v[58:59]
	v_pk_fma_f32 v[90:91], v[74:75], v[146:147], v[90:91]
	v_pk_fma_f32 v[86:87], v[70:71], v[146:147], v[86:87]
	v_pk_fma_f32 v[82:83], v[66:67], v[146:147], v[82:83]
	s_mov_b32 s2, 0xc000
	s_waitcnt vmcnt(20) lgkmcnt(0)
	global_store_dwordx2 v[92:93], v[148:149], off offset:-4096
	s_nop 0
	v_pk_fma_f32 v[88:89], v[74:75], v[148:149], v[88:89]
	v_pk_fma_f32 v[84:85], v[70:71], v[148:149], v[84:85]
	v_pk_fma_f32 v[96:97], v[36:37], v[148:149], v[96:97]
	v_pk_fma_f32 v[58:59], v[66:67], v[148:149], v[58:59]
	v_pk_fma_f32 v[82:83], v[68:69], v[148:149], v[82:83]
	v_pk_fma_f32 v[86:87], v[72:73], v[148:149], v[86:87]
	v_pk_fma_f32 v[90:91], v[76:77], v[148:149], v[90:91]
	s_waitcnt vmcnt(20) lgkmcnt(0)
	global_store_dwordx2 v[92:93], v[150:151], off
	v_pk_fma_f32 v[92:93], v[76:77], v[150:151], v[88:89]
	v_add_co_u32_e32 v88, vcc, s8, v34
	v_pk_fma_f32 v[84:85], v[72:73], v[150:151], v[84:85]
	s_nop 0
	v_addc_co_u32_e32 v89, vcc, 0, v35, vcc
	s_nop 0
	v_add_co_u32_e32 v88, vcc, s35, v2
	v_pk_fma_f32 v[96:97], v[38:39], v[150:151], v[96:97]
	s_nop 0
	v_addc_co_u32_e32 v89, vcc, 0, v3, vcc
	v_add_co_u32_e32 v104, vcc, s59, v34
	s_mov_b32 s35, 0x16267000
	s_nop 0
	v_addc_co_u32_e32 v105, vcc, 0, v35, vcc
	v_pk_fma_f32 v[58:59], v[68:69], v[150:151], v[58:59]
	v_pk_fma_f32 v[82:83], v[70:71], v[150:151], v[82:83]
	v_pk_fma_f32 v[86:87], v[74:75], v[150:151], v[86:87]
	s_mov_b32 s8, 0x14000
	s_waitcnt vmcnt(20) lgkmcnt(0)
	global_store_dwordx2 v[88:89], v[152:153], off offset:-4096
	s_nop 0
	v_pk_fma_f32 v[84:85], v[74:75], v[152:153], v[84:85]
	v_pk_fma_f32 v[96:97], v[40:41], v[152:153], v[96:97]
	v_pk_fma_f32 v[58:59], v[70:71], v[152:153], v[58:59]
	v_pk_fma_f32 v[82:83], v[72:73], v[152:153], v[82:83]
	v_pk_fma_f32 v[86:87], v[76:77], v[152:153], v[86:87]
	s_waitcnt vmcnt(20) lgkmcnt(0)
	global_store_dwordx2 v[88:89], v[154:155], off
	v_pk_fma_f32 v[88:89], v[76:77], v[154:155], v[84:85]
	v_add_co_u32_e32 v84, vcc, s51, v34
	v_pk_fma_f32 v[96:97], v[42:43], v[154:155], v[96:97]
	s_nop 0
	v_addc_co_u32_e32 v85, vcc, 0, v35, vcc
	s_nop 0
	v_add_co_u32_e32 v84, vcc, s35, v2
	v_pk_fma_f32 v[58:59], v[72:73], v[154:155], v[58:59]
	s_nop 0
	v_addc_co_u32_e32 v85, vcc, 0, v3, vcc
	s_mov_b32 s35, 0x16269000
	v_pk_fma_f32 v[82:83], v[74:75], v[154:155], v[82:83]
	s_waitcnt vmcnt(20) lgkmcnt(0)
	v_pk_fma_f32 v[110:111], v[44:45], v[156:157], v[96:97]
	v_add_co_u32_e32 v96, vcc, s60, v34
	global_store_dwordx2 v[84:85], v[156:157], off offset:-4096
	s_nop 0
	v_addc_co_u32_e32 v97, vcc, 0, v35, vcc
	s_nop 0
	v_pk_fma_f32 v[58:59], v[74:75], v[156:157], v[58:59]
	v_pk_fma_f32 v[82:83], v[76:77], v[156:157], v[82:83]
	s_waitcnt vmcnt(20) lgkmcnt(0)
	global_store_dwordx2 v[84:85], v[158:159], off
	v_pk_fma_f32 v[84:85], v[76:77], v[158:159], v[58:59]
	v_add_co_u32_e32 v58, vcc, s27, v34
	v_pk_fma_f32 v[110:111], v[46:47], v[158:159], v[110:111]
	s_nop 0
	v_addc_co_u32_e32 v59, vcc, 0, v35, vcc
	s_nop 0
	v_add_co_u32_e32 v58, vcc, s35, v2
	s_mov_b32 s35, 0x1626b000
	s_nop 0
	v_addc_co_u32_e32 v59, vcc, 0, v3, vcc
	v_add_co_u32_e32 v62, vcc, s61, v34
	s_mov_b32 s27, 0x16000
	s_nop 0
	v_addc_co_u32_e32 v63, vcc, 0, v35, vcc
	s_waitcnt vmcnt(20) lgkmcnt(0)
	global_store_dwordx2 v[58:59], v[160:161], off offset:-4096
	v_pk_fma_f32 v[60:61], v[48:49], v[160:161], v[110:111]
	s_nop 0
	s_waitcnt vmcnt(20) lgkmcnt(0)
	global_store_dwordx2 v[58:59], v[162:163], off
	v_pk_fma_f32 v[58:59], v[50:51], v[162:163], v[60:61]
	v_add_co_u32_e32 v60, vcc, s46, v34
	s_nop 1
	v_addc_co_u32_e32 v61, vcc, 0, v35, vcc
	s_nop 0
	v_add_co_u32_e32 v60, vcc, s35, v2
	s_mov_b32 s35, 0x1626d000
	s_nop 0
	v_addc_co_u32_e32 v61, vcc, 0, v3, vcc
	v_add_co_u32_e32 v62, vcc, s82, v34
	s_waitcnt vmcnt(20) lgkmcnt(0)
	global_store_dwordx2 v[60:61], v[164:165], off offset:-4096
	v_addc_co_u32_e32 v63, vcc, 0, v35, vcc
	s_nop 0
	v_pk_fma_f32 v[62:63], v[56:57], v[148:149], v[102:103]
	v_pk_fma_f32 v[58:59], v[52:53], v[164:165], v[58:59]
	v_pk_fma_f32 v[62:63], v[36:37], v[150:151], v[62:63]
	s_waitcnt vmcnt(20) lgkmcnt(0)
	global_store_dwordx2 v[60:61], v[166:167], off
	v_add_co_u32_e32 v60, vcc, s47, v34
	v_pk_fma_f32 v[62:63], v[38:39], v[152:153], v[62:63]
	s_nop 0
	v_addc_co_u32_e32 v61, vcc, 0, v35, vcc
	s_nop 0
	v_pk_fma_f32 v[62:63], v[40:41], v[154:155], v[62:63]
	v_add_co_u32_e32 v60, vcc, s35, v2
	v_pk_fma_f32 v[62:63], v[42:43], v[156:157], v[62:63]
	s_nop 0
	v_addc_co_u32_e32 v61, vcc, 0, v3, vcc
	v_pk_fma_f32 v[62:63], v[44:45], v[158:159], v[62:63]
	s_mov_b32 s35, 0x1626f000
	v_pk_fma_f32 v[62:63], v[46:47], v[160:161], v[62:63]
	v_pk_fma_f32 v[58:59], v[54:55], v[166:167], v[58:59]
	v_pk_fma_f32 v[62:63], v[48:49], v[162:163], v[62:63]
	s_waitcnt vmcnt(20) lgkmcnt(0)
	global_store_dwordx2 v[60:61], v[168:169], off offset:-4096
	v_pk_fma_f32 v[62:63], v[50:51], v[164:165], v[62:63]
	v_pk_fma_f32 v[58:59], v[30:31], v[168:169], v[58:59]
	v_pk_fma_f32 v[62:63], v[52:53], v[166:167], v[62:63]
	s_nop 0
	v_pk_fma_f32 v[76:77], v[54:55], v[168:169], v[62:63]
	v_add_co_u32_e32 v62, vcc, s83, v34
	s_nop 1
	v_addc_co_u32_e32 v63, vcc, 0, v35, vcc
	s_nop 0
	v_pk_fma_f32 v[62:63], v[56:57], v[152:153], v[92:93]
	s_waitcnt vmcnt(20) lgkmcnt(0)
	global_store_dwordx2 v[60:61], v[178:179], off
	v_pk_fma_f32 v[60:61], v[56:57], v[150:151], v[90:91]
	v_pk_fma_f32 v[58:59], v[4:5], v[178:179], v[58:59]
	v_pk_fma_f32 v[60:61], v[36:37], v[152:153], v[60:61]
	v_pk_fma_f32 v[62:63], v[36:37], v[154:155], v[62:63]
	v_pk_fma_f32 v[60:61], v[38:39], v[154:155], v[60:61]
	v_pk_fma_f32 v[62:63], v[38:39], v[156:157], v[62:63]
	v_pk_fma_f32 v[60:61], v[40:41], v[156:157], v[60:61]
	v_pk_fma_f32 v[62:63], v[40:41], v[158:159], v[62:63]
	v_pk_fma_f32 v[60:61], v[42:43], v[158:159], v[60:61]
	v_pk_fma_f32 v[62:63], v[42:43], v[160:161], v[62:63]
	v_pk_fma_f32 v[60:61], v[44:45], v[160:161], v[60:61]
	v_pk_fma_f32 v[62:63], v[44:45], v[162:163], v[62:63]
	v_pk_fma_f32 v[60:61], v[46:47], v[162:163], v[60:61]
	v_pk_fma_f32 v[62:63], v[46:47], v[164:165], v[62:63]
	v_pk_fma_f32 v[60:61], v[48:49], v[164:165], v[60:61]
	v_pk_fma_f32 v[62:63], v[48:49], v[166:167], v[62:63]
	v_pk_fma_f32 v[60:61], v[50:51], v[166:167], v[60:61]
	v_pk_fma_f32 v[62:63], v[50:51], v[168:169], v[62:63]
	v_pk_fma_f32 v[60:61], v[52:53], v[168:169], v[60:61]
	v_pk_fma_f32 v[62:63], v[52:53], v[178:179], v[62:63]
	v_pk_fma_f32 v[68:69], v[54:55], v[178:179], v[60:61]
	v_add_co_u32_e32 v60, vcc, s3, v34
	s_nop 1
	v_addc_co_u32_e32 v61, vcc, 0, v35, vcc
	s_nop 0
	v_add_co_u32_e32 v60, vcc, s35, v2
	s_mov_b32 s35, 0x16271000
	s_nop 0
	v_addc_co_u32_e32 v61, vcc, 0, v3, vcc
	v_add_co_u32_e32 v64, vcc, s90, v34
	s_waitcnt vmcnt(20) lgkmcnt(0)
	global_store_dwordx2 v[60:61], v[180:181], off offset:-4096
	v_addc_co_u32_e32 v65, vcc, 0, v35, vcc
	s_nop 0
	v_add_co_u32_e32 v64, vcc, s48, v34
	v_pk_fma_f32 v[58:59], v[6:7], v[180:181], v[58:59]
	s_nop 0
	v_addc_co_u32_e32 v65, vcc, 0, v35, vcc
	v_add_co_u32_e32 v66, vcc, s35, v2
	s_mov_b32 s35, 0x16273000
	s_nop 0
	v_addc_co_u32_e32 v67, vcc, 0, v3, vcc
	v_add_co_u32_e32 v70, vcc, s52, v34
	v_pk_fma_f32 v[62:63], v[54:55], v[180:181], v[62:63]
	s_nop 0
	v_addc_co_u32_e32 v71, vcc, 0, v35, vcc
	s_waitcnt vmcnt(20) lgkmcnt(0)
	global_store_dwordx2 v[60:61], v[182:183], off
	s_nop 0
	v_pk_fma_f32 v[60:61], v[8:9], v[182:183], v[58:59]
	v_pk_fma_f32 v[58:59], v[56:57], v[154:155], v[86:87]
	s_waitcnt vmcnt(20) lgkmcnt(0)
	global_store_dwordx2 v[66:67], v[184:185], off offset:-4096
	s_nop 0
	v_pk_fma_f32 v[72:73], v[10:11], v[184:185], v[60:61]
	v_pk_fma_f32 v[60:61], v[56:57], v[156:157], v[88:89]
	v_pk_fma_f32 v[58:59], v[36:37], v[156:157], v[58:59]
	v_pk_fma_f32 v[60:61], v[36:37], v[158:159], v[60:61]
	v_pk_fma_f32 v[58:59], v[38:39], v[158:159], v[58:59]
	v_pk_fma_f32 v[60:61], v[38:39], v[160:161], v[60:61]
	v_pk_fma_f32 v[58:59], v[40:41], v[160:161], v[58:59]
	v_pk_fma_f32 v[60:61], v[40:41], v[162:163], v[60:61]
	v_pk_fma_f32 v[58:59], v[42:43], v[162:163], v[58:59]
	v_pk_fma_f32 v[60:61], v[42:43], v[164:165], v[60:61]
	v_pk_fma_f32 v[58:59], v[44:45], v[164:165], v[58:59]
	v_pk_fma_f32 v[60:61], v[44:45], v[166:167], v[60:61]
	v_pk_fma_f32 v[58:59], v[46:47], v[166:167], v[58:59]
	v_pk_fma_f32 v[60:61], v[46:47], v[168:169], v[60:61]
	v_pk_fma_f32 v[58:59], v[48:49], v[168:169], v[58:59]
	v_pk_fma_f32 v[60:61], v[48:49], v[178:179], v[60:61]
	v_pk_fma_f32 v[58:59], v[50:51], v[178:179], v[58:59]
	v_pk_fma_f32 v[60:61], v[50:51], v[180:181], v[60:61]
	v_pk_fma_f32 v[58:59], v[52:53], v[180:181], v[58:59]
	v_pk_fma_f32 v[60:61], v[52:53], v[182:183], v[60:61]
	v_pk_fma_f32 v[58:59], v[54:55], v[182:183], v[58:59]
	v_pk_fma_f32 v[60:61], v[54:55], v[184:185], v[60:61]
	v_pk_fma_f32 v[58:59], v[30:31], v[184:185], v[58:59]
	s_waitcnt vmcnt(20) lgkmcnt(0)
	v_pk_fma_f32 v[86:87], v[12:13], v[186:187], v[72:73]
	v_add_co_u32_e32 v72, vcc, s49, v34
	global_store_dwordx2 v[66:67], v[186:187], off
	s_nop 0
	v_addc_co_u32_e32 v73, vcc, 0, v35, vcc
	s_nop 0
	v_pk_fma_f32 v[66:67], v[56:57], v[158:159], v[82:83]
	v_add_co_u32_e32 v82, vcc, s35, v2
	v_pk_fma_f32 v[56:57], v[56:57], v[160:161], v[84:85]
	v_pk_fma_f32 v[66:67], v[36:37], v[160:161], v[66:67]
	v_addc_co_u32_e32 v83, vcc, 0, v3, vcc
	v_pk_fma_f32 v[36:37], v[36:37], v[162:163], v[56:57]
	v_pk_fma_f32 v[66:67], v[38:39], v[162:163], v[66:67]
	v_pk_fma_f32 v[36:37], v[38:39], v[164:165], v[36:37]
	v_add_co_u32_e32 v38, vcc, s88, v34
	v_pk_fma_f32 v[66:67], v[40:41], v[164:165], v[66:67]
	s_nop 0
	v_addc_co_u32_e32 v39, vcc, 0, v35, vcc
	v_pk_fma_f32 v[36:37], v[40:41], v[166:167], v[36:37]
	v_add_co_u32_e32 v40, vcc, s50, v34
	v_pk_fma_f32 v[66:67], v[42:43], v[166:167], v[66:67]
	s_nop 0
	v_addc_co_u32_e32 v41, vcc, 0, v35, vcc
	v_pk_fma_f32 v[36:37], v[42:43], v[168:169], v[36:37]
	s_mov_b32 s35, 0x16275000
	v_pk_fma_f32 v[66:67], v[44:45], v[168:169], v[66:67]
	v_pk_fma_f32 v[36:37], v[44:45], v[178:179], v[36:37]
	v_add_co_u32_e32 v44, vcc, s35, v2
	v_pk_fma_f32 v[66:67], v[46:47], v[178:179], v[66:67]
	s_nop 0
	v_addc_co_u32_e32 v45, vcc, 0, v3, vcc
	v_add_co_u32_e32 v34, vcc, s89, v34
	v_pk_fma_f32 v[36:37], v[46:47], v[180:181], v[36:37]
	s_nop 0
	v_addc_co_u32_e32 v35, vcc, 0, v35, vcc
	v_pk_fma_f32 v[66:67], v[48:49], v[180:181], v[66:67]
	v_pk_fma_f32 v[36:37], v[48:49], v[182:183], v[36:37]
	v_pk_fma_f32 v[66:67], v[50:51], v[182:183], v[66:67]
	v_pk_fma_f32 v[36:37], v[50:51], v[184:185], v[36:37]
	v_pk_fma_f32 v[66:67], v[52:53], v[184:185], v[66:67]
	v_pk_fma_f32 v[36:37], v[52:53], v[186:187], v[36:37]
	v_pk_fma_f32 v[66:67], v[54:55], v[186:187], v[66:67]
	v_pk_fma_f32 v[58:59], v[4:5], v[186:187], v[58:59]
	v_pk_fma_f32 v[60:61], v[30:31], v[186:187], v[60:61]
	s_waitcnt vmcnt(20) lgkmcnt(0)
	global_store_dwordx2 v[82:83], v[188:189], off offset:-4096
	s_nop 0
	v_pk_fma_f32 v[86:87], v[14:15], v[188:189], v[86:87]
	v_pk_fma_f32 v[36:37], v[54:55], v[188:189], v[36:37]
	v_pk_fma_f32 v[58:59], v[6:7], v[188:189], v[58:59]
	v_pk_fma_f32 v[60:61], v[4:5], v[188:189], v[60:61]
	v_pk_fma_f32 v[66:67], v[30:31], v[188:189], v[66:67]
	s_waitcnt vmcnt(20) lgkmcnt(0)
	global_store_dwordx2 v[82:83], v[190:191], off
	s_nop 0
	v_pk_fma_f32 v[42:43], v[16:17], v[190:191], v[86:87]
	v_pk_fma_f32 v[66:67], v[4:5], v[190:191], v[66:67]
	v_pk_fma_f32 v[60:61], v[6:7], v[190:191], v[60:61]
	v_pk_fma_f32 v[58:59], v[8:9], v[190:191], v[58:59]
	s_waitcnt vmcnt(20) lgkmcnt(0)
	global_store_dwordx2 v[44:45], v[192:193], off offset:-4096
	s_nop 0
	v_pk_fma_f32 v[42:43], v[24:25], v[192:193], v[42:43]
	v_pk_fma_f32 v[66:67], v[6:7], v[192:193], v[66:67]
	v_pk_fma_f32 v[60:61], v[8:9], v[192:193], v[60:61]
	v_pk_fma_f32 v[58:59], v[10:11], v[192:193], v[58:59]
	s_waitcnt vmcnt(20) lgkmcnt(0)
	global_store_dwordx2 v[44:45], v[194:195], off
	v_pk_fma_f32 v[44:45], v[26:27], v[194:195], v[42:43]
	v_add_co_u32_e32 v42, vcc, s14, v32
	s_mov_b32 s14, 0xe003000
	s_nop 0
	v_addc_co_u32_e32 v43, vcc, 0, v33, vcc
	global_load_dword v47, v[42:43], off offset:2048
	v_add_co_u32_e32 v42, vcc, s14, v32
	s_mov_b32 s14, 0x16277000
	s_nop 0
	v_addc_co_u32_e32 v43, vcc, 0, v33, vcc
	global_load_dword v48, v[42:43], off
	v_pk_fma_f32 v[66:67], v[8:9], v[194:195], v[66:67]
	v_pk_fma_f32 v[60:61], v[10:11], v[194:195], v[60:61]
	v_pk_fma_f32 v[58:59], v[12:13], v[194:195], v[58:59]
	s_waitcnt vmcnt(1)
	v_lshlrev_b32_e32 v42, 16, v47
	v_and_b32_e32 v43, 0xffff0000, v47
	s_waitcnt vmcnt(0)
	v_lshlrev_b32_e32 v46, 16, v48
	v_and_b32_e32 v47, 0xffff0000, v48
	v_add_co_u32_e32 v48, vcc, s14, v2
	s_mov_b32 s14, 0xe009000
	s_nop 0
	v_addc_co_u32_e32 v49, vcc, 0, v3, vcc
	v_pk_mul_f32 v[42:43], v[42:43], v[46:47]
	v_add_co_u32_e32 v46, vcc, s14, v32
	global_store_dwordx2 v[48:49], v[42:43], off offset:-4096
	s_nop 0
	v_addc_co_u32_e32 v47, vcc, 0, v33, vcc
	s_mov_b32 s14, 0xe00a000
	global_load_dword v51, v[46:47], off offset:2048
	v_add_co_u32_e32 v46, vcc, s14, v32
	s_mov_b32 s14, 0xe010000
	s_nop 0
	v_addc_co_u32_e32 v47, vcc, 0, v33, vcc
	global_load_dword v52, v[46:47], off
	v_pk_fma_f32 v[66:67], v[10:11], v[42:43], v[66:67]
	v_pk_fma_f32 v[60:61], v[12:13], v[42:43], v[60:61]
	v_pk_fma_f32 v[58:59], v[14:15], v[42:43], v[58:59]
	v_pk_fma_f32 v[44:45], v[28:29], v[42:43], v[44:45]
	s_waitcnt vmcnt(1)
	v_lshlrev_b32_e32 v46, 16, v51
	v_and_b32_e32 v47, 0xffff0000, v51
	s_waitcnt vmcnt(0)
	v_lshlrev_b32_e32 v50, 16, v52
	v_and_b32_e32 v51, 0xffff0000, v52
	v_pk_mul_f32 v[46:47], v[46:47], v[50:51]
	v_add_co_u32_e32 v50, vcc, s14, v32
	global_store_dwordx2 v[48:49], v[46:47], off
	s_nop 0
	v_addc_co_u32_e32 v51, vcc, 0, v33, vcc
	s_mov_b32 s14, 0xe011000
	global_load_dword v53, v[50:51], off offset:2048
	v_add_co_u32_e32 v50, vcc, s14, v32
	s_mov_b32 s14, 0x16279000
	s_nop 0
	v_addc_co_u32_e32 v51, vcc, 0, v33, vcc
	global_load_dword v54, v[50:51], off
	v_add_co_u32_e32 v56, vcc, s14, v2
	s_mov_b32 s14, 0xe017000
	s_nop 0
	v_addc_co_u32_e32 v57, vcc, 0, v3, vcc
	v_pk_fma_f32 v[48:49], v[30:31], v[178:179], v[76:77]
	v_pk_fma_f32 v[66:67], v[12:13], v[46:47], v[66:67]
	v_pk_fma_f32 v[48:49], v[4:5], v[180:181], v[48:49]
	v_pk_fma_f32 v[60:61], v[14:15], v[46:47], v[60:61]
	v_pk_fma_f32 v[48:49], v[6:7], v[182:183], v[48:49]
	v_pk_fma_f32 v[58:59], v[16:17], v[46:47], v[58:59]
	v_pk_fma_f32 v[48:49], v[8:9], v[184:185], v[48:49]
	s_waitcnt vmcnt(1)
	v_lshlrev_b32_e32 v50, 16, v53
	v_and_b32_e32 v51, 0xffff0000, v53
	v_pk_fma_f32 v[48:49], v[10:11], v[186:187], v[48:49]
	s_waitcnt vmcnt(0)
	v_lshlrev_b32_e32 v52, 16, v54
	v_and_b32_e32 v53, 0xffff0000, v54
	v_pk_mul_f32 v[50:51], v[50:51], v[52:53]
	v_add_co_u32_e32 v54, vcc, s14, v32
	global_store_dwordx2 v[56:57], v[50:51], off offset:-4096
	s_nop 0
	v_addc_co_u32_e32 v55, vcc, 0, v33, vcc
	s_mov_b32 s14, 0xe018000
	v_pk_fma_f32 v[52:53], v[30:31], v[180:181], v[68:69]
	global_load_dword v69, v[54:55], off offset:2048
	v_add_co_u32_e32 v54, vcc, s14, v32
	s_mov_b32 s14, 0xe01e000
	s_nop 0
	v_addc_co_u32_e32 v55, vcc, 0, v33, vcc
	global_load_dword v76, v[54:55], off
	v_pk_fma_f32 v[52:53], v[4:5], v[182:183], v[52:53]
	v_pk_fma_f32 v[48:49], v[12:13], v[188:189], v[48:49]
	v_pk_fma_f32 v[52:53], v[6:7], v[184:185], v[52:53]
	v_pk_fma_f32 v[48:49], v[14:15], v[190:191], v[48:49]
	v_pk_fma_f32 v[52:53], v[8:9], v[186:187], v[52:53]
	v_pk_fma_f32 v[48:49], v[16:17], v[192:193], v[48:49]
	v_pk_fma_f32 v[52:53], v[10:11], v[188:189], v[52:53]
	v_pk_fma_f32 v[66:67], v[14:15], v[50:51], v[66:67]
	v_pk_fma_f32 v[52:53], v[12:13], v[190:191], v[52:53]
	v_pk_fma_f32 v[48:49], v[24:25], v[194:195], v[48:49]
	v_pk_fma_f32 v[52:53], v[14:15], v[192:193], v[52:53]
	v_pk_fma_f32 v[60:61], v[16:17], v[50:51], v[60:61]
	v_pk_fma_f32 v[52:53], v[16:17], v[194:195], v[52:53]
	v_pk_fma_f32 v[48:49], v[26:27], v[42:43], v[48:49]
	v_pk_fma_f32 v[52:53], v[24:25], v[42:43], v[52:53]
	v_pk_fma_f32 v[58:59], v[24:25], v[50:51], v[58:59]
	v_pk_fma_f32 v[48:49], v[28:29], v[46:47], v[48:49]
	v_pk_fma_f32 v[52:53], v[26:27], v[46:47], v[52:53]
	s_waitcnt vmcnt(1)
	v_lshlrev_b32_e32 v54, 16, v69
	v_and_b32_e32 v55, 0xffff0000, v69
	v_pk_fma_f32 v[52:53], v[28:29], v[50:51], v[52:53]
	s_waitcnt vmcnt(0)
	v_lshlrev_b32_e32 v68, 16, v76
	v_and_b32_e32 v69, 0xffff0000, v76
	v_pk_mul_f32 v[54:55], v[54:55], v[68:69]
	global_store_dwordx2 v[56:57], v[54:55], off
	v_pk_fma_f32 v[56:57], v[30:31], v[182:183], v[62:63]
	v_add_co_u32_e32 v62, vcc, s14, v32
	s_mov_b32 s14, 0xe01f000
	s_nop 0
	v_addc_co_u32_e32 v63, vcc, 0, v33, vcc
	global_load_dword v69, v[62:63], off offset:2048
	v_add_co_u32_e32 v62, vcc, s14, v32
	s_mov_b32 s14, 0x1627b000
	s_nop 0
	v_addc_co_u32_e32 v63, vcc, 0, v33, vcc
	global_load_dword v74, v[62:63], off
	v_pk_fma_f32 v[56:57], v[4:5], v[184:185], v[56:57]
	v_pk_fma_f32 v[66:67], v[16:17], v[54:55], v[66:67]
	v_pk_fma_f32 v[56:57], v[6:7], v[186:187], v[56:57]
	v_pk_fma_f32 v[60:61], v[24:25], v[54:55], v[60:61]
	v_pk_fma_f32 v[56:57], v[8:9], v[188:189], v[56:57]
	v_pk_fma_f32 v[58:59], v[26:27], v[54:55], v[58:59]
	v_pk_fma_f32 v[56:57], v[10:11], v[190:191], v[56:57]
	s_waitcnt vmcnt(1)
	v_lshlrev_b32_e32 v62, 16, v69
	v_and_b32_e32 v63, 0xffff0000, v69
	v_pk_fma_f32 v[56:57], v[12:13], v[192:193], v[56:57]
	s_waitcnt vmcnt(0)
	v_lshlrev_b32_e32 v68, 16, v74
	v_and_b32_e32 v69, 0xffff0000, v74
	v_pk_mul_f32 v[62:63], v[62:63], v[68:69]
	v_add_co_u32_e32 v68, vcc, s14, v2
	s_mov_b32 s14, 0xe025000
	s_nop 0
	v_addc_co_u32_e32 v69, vcc, 0, v3, vcc
	v_add_co_u32_e32 v64, vcc, s14, v32
	global_store_dwordx2 v[68:69], v[62:63], off offset:-4096
	s_nop 0
	v_addc_co_u32_e32 v65, vcc, 0, v33, vcc
	s_mov_b32 s14, 0xe026000
	global_load_dword v75, v[64:65], off offset:2048
	v_add_co_u32_e32 v64, vcc, s14, v32
	s_mov_b32 s14, 0xe02c000
	s_nop 0
	v_addc_co_u32_e32 v65, vcc, 0, v33, vcc
	global_load_dword v76, v[64:65], off
	v_pk_fma_f32 v[56:57], v[14:15], v[194:195], v[56:57]
	v_pk_fma_f32 v[66:67], v[24:25], v[62:63], v[66:67]
	v_pk_fma_f32 v[56:57], v[16:17], v[42:43], v[56:57]
	v_pk_fma_f32 v[60:61], v[26:27], v[62:63], v[60:61]
	v_pk_fma_f32 v[56:57], v[24:25], v[46:47], v[56:57]
	v_pk_fma_f32 v[58:59], v[28:29], v[62:63], v[58:59]
	v_pk_fma_f32 v[56:57], v[26:27], v[50:51], v[56:57]
	s_waitcnt vmcnt(1)
	v_lshlrev_b32_e32 v64, 16, v75
	v_and_b32_e32 v65, 0xffff0000, v75
	v_pk_fma_f32 v[56:57], v[28:29], v[54:55], v[56:57]
	s_waitcnt vmcnt(0)
	v_lshlrev_b32_e32 v74, 16, v76
	v_and_b32_e32 v75, 0xffff0000, v76
	v_pk_mul_f32 v[64:65], v[64:65], v[74:75]
	global_store_dwordx2 v[68:69], v[64:65], off
	v_add_co_u32_e32 v68, vcc, s14, v32
	s_mov_b32 s14, 0xe02d000
	s_nop 0
	v_addc_co_u32_e32 v69, vcc, 0, v33, vcc
	global_load_dword v71, v[68:69], off offset:2048
	v_add_co_u32_e32 v68, vcc, s14, v32
	s_mov_b32 s14, 0x1627d000
	s_nop 0
	v_addc_co_u32_e32 v69, vcc, 0, v33, vcc
	global_load_dword v74, v[68:69], off
	v_add_co_u32_e32 v2, vcc, s14, v2
	s_mov_b32 s14, 0xe033000
	s_nop 0
	v_addc_co_u32_e32 v3, vcc, 0, v3, vcc
	v_pk_fma_f32 v[66:67], v[26:27], v[64:65], v[66:67]
	v_pk_fma_f32 v[60:61], v[28:29], v[64:65], v[60:61]
	s_waitcnt vmcnt(1)
	v_lshlrev_b32_e32 v68, 16, v71
	v_and_b32_e32 v69, 0xffff0000, v71
	s_waitcnt vmcnt(0)
	v_lshlrev_b32_e32 v70, 16, v74
	v_and_b32_e32 v71, 0xffff0000, v74
	v_pk_mul_f32 v[68:69], v[68:69], v[70:71]
	v_add_co_u32_e32 v70, vcc, s14, v32
	s_mov_b32 s14, 0xe034000
	s_nop 0
	v_addc_co_u32_e32 v71, vcc, 0, v33, vcc
	v_add_co_u32_e32 v32, vcc, s14, v32
	global_store_dwordx2 v[2:3], v[68:69], off offset:-4096
	s_nop 0
	v_addc_co_u32_e32 v33, vcc, 0, v33, vcc
	global_load_dword v71, v[70:71], off offset:2048
	s_andn2_b64 vcc, exec, s[56:57]
	global_load_dword v72, v[32:33], off
	v_pk_fma_f32 v[66:67], v[28:29], v[68:69], v[66:67]
	s_waitcnt vmcnt(1)
	v_lshlrev_b32_e32 v32, 16, v71
	v_and_b32_e32 v33, 0xffff0000, v71
	s_waitcnt vmcnt(0)
	v_lshlrev_b32_e32 v70, 16, v72
	v_and_b32_e32 v71, 0xffff0000, v72
	v_pk_mul_f32 v[32:33], v[32:33], v[70:71]
	global_store_dwordx2 v[2:3], v[32:33], off
	v_pk_fma_f32 v[2:3], v[30:31], v[190:191], v[36:37]
	s_nop 0
	v_pk_fma_f32 v[2:3], v[4:5], v[192:193], v[2:3]
	v_lshl_add_u32 v4, v122, 3, 0
	v_pk_fma_f32 v[2:3], v[6:7], v[194:195], v[2:3]
	s_nop 0
	v_pk_fma_f32 v[2:3], v[8:9], v[42:43], v[2:3]
	s_nop 0
	v_pk_fma_f32 v[2:3], v[10:11], v[46:47], v[2:3]
	s_nop 0
	v_pk_fma_f32 v[2:3], v[12:13], v[50:51], v[2:3]
	s_nop 0
	v_pk_fma_f32 v[2:3], v[14:15], v[54:55], v[2:3]
	s_nop 0
	v_pk_fma_f32 v[2:3], v[16:17], v[62:63], v[2:3]
	s_nop 0
	v_pk_fma_f32 v[2:3], v[24:25], v[64:65], v[2:3]
	s_nop 0
	v_pk_fma_f32 v[2:3], v[26:27], v[68:69], v[2:3]
	s_nop 0
	v_pk_fma_f32 v[2:3], v[28:29], v[32:33], v[2:3]
	ds_write2st64_b64 v4, v[44:45], v[48:49] offset1:8
	ds_write2st64_b64 v4, v[52:53], v[56:57] offset0:16 offset1:24
	ds_write2st64_b64 v4, v[58:59], v[60:61] offset0:32 offset1:40
	ds_write2st64_b64 v4, v[66:67], v[2:3] offset0:48 offset1:56
	s_waitcnt lgkmcnt(0)
	s_barrier
	s_cbranch_vccnz .LBB0_638
	v_readlane_b32 s14, v243, 3
	v_and_b32_e32 v2, 64, v203
	v_add_u32_e32 v32, 64, v2
	v_add_u32_e32 v25, s14, v19
	ds_read_b128 v[14:17], v25
	ds_read_b128 v[10:13], v25 offset:16
	v_xor_b32_e32 v2, 1, v203
	v_cmp_lt_i32_e32 vcc, v2, v32
	ds_read_b128 v[6:9], v25 offset:2048
	s_waitcnt lgkmcnt(2)
	v_mov_b32_e32 v3, v16
	v_cndmask_b32_e32 v2, v203, v2, vcc
	v_lshlrev_b32_e32 v33, 2, v2
	v_mov_b32_e32 v2, v15
	v_mov_b32_e32 v4, v14
	v_mov_b32_e32 v5, v17
	v_pk_add_f32 v[2:3], v[2:3], v[4:5]
	s_waitcnt lgkmcnt(1)
	v_mov_b32_e32 v26, v11
	v_add_f32_e32 v2, v2, v3
	v_add_f32_e32 v24, 0, v2
	ds_read_b128 v[2:5], v25 offset:2064
	v_mov_b32_e32 v27, v12
	v_mov_b32_e32 v28, v10
	v_mov_b32_e32 v29, v13
	v_pk_add_f32 v[26:27], v[26:27], v[28:29]
	s_waitcnt lgkmcnt(1)
	v_add_f32_e32 v28, v6, v7
	v_pk_add_f32 v[26:27], v[26:27], v[26:27] op_sel:[0,1] op_sel_hi:[1,0]
	v_add_f32_e32 v30, v8, v9
	s_waitcnt lgkmcnt(0)
	v_mov_b32_e32 v25, v2
	v_mov_b32_e32 v27, v3
	v_mov_b32_e32 v29, v4
	v_mov_b32_e32 v31, v5
	v_pk_add_f32 v[24:25], v[24:25], v[26:27]
	v_pk_add_f32 v[26:27], v[28:29], v[30:31]
	s_add_u32 s22, s22, s0
	v_pk_add_f32 v[24:25], v[24:25], v[26:27]
	v_xor_b32_e32 v26, 2, v203
	v_add_f32_e32 v24, v24, v25
	ds_bpermute_b32 v25, v33, v24
	v_cmp_lt_i32_e32 vcc, v26, v32
	s_addc_u32 s23, s23, s1
	s_add_u32 s0, s34, s0
	v_cndmask_b32_e32 v26, v203, v26, vcc
	v_lshlrev_b32_e32 v36, 2, v26
	s_waitcnt lgkmcnt(0)
	v_add_f32_e32 v24, v24, v25
	ds_bpermute_b32 v25, v36, v24
	v_xor_b32_e32 v26, 4, v203
	v_cmp_lt_i32_e32 vcc, v26, v32
	s_addc_u32 s1, s19, s1
	v_readlane_b32 s14, v244, 27
	v_cndmask_b32_e32 v26, v203, v26, vcc
	v_lshlrev_b32_e32 v37, 2, v26
	s_waitcnt lgkmcnt(0)
	v_add_f32_e32 v24, v24, v25
	ds_bpermute_b32 v25, v37, v24
	v_xor_b32_e32 v26, 8, v203
	v_cmp_lt_i32_e32 vcc, v26, v32
	s_add_u32 s14, s28, s14
	s_addc_u32 s15, s18, 0
	v_cndmask_b32_e32 v26, v203, v26, vcc
	v_lshlrev_b32_e32 v38, 2, v26
	s_waitcnt lgkmcnt(0)
	v_add_f32_e32 v24, v24, v25
	ds_bpermute_b32 v25, v38, v24
	v_xor_b32_e32 v26, 16, v203
	v_cmp_lt_i32_e32 vcc, v26, v32
	s_mul_i32 s18, s15, 0x7000
	s_mul_hi_u32 s19, s14, 0x7000
	v_cndmask_b32_e32 v26, v203, v26, vcc
	v_lshlrev_b32_e32 v39, 2, v26
	s_waitcnt lgkmcnt(0)
	v_add_f32_e32 v24, v24, v25
	ds_bpermute_b32 v25, v39, v24
	v_xor_b32_e32 v26, 32, v203
	v_cmp_lt_i32_e32 vcc, v26, v32
	s_add_i32 s19, s19, s18
	s_mul_i32 s18, s14, 0x7000
	v_cndmask_b32_e32 v26, v203, v26, vcc
	v_lshlrev_b32_e32 v48, 2, v26
	s_waitcnt lgkmcnt(0)
	v_add_f32_e32 v24, v24, v25
	ds_bpermute_b32 v25, v48, v24
	s_add_u32 s18, s92, s18
	s_addc_u32 s19, s93, s19
	v_lshlrev_b32_e32 v172, 2, v125
	s_add_u32 s18, s18, 0x3800
	s_waitcnt lgkmcnt(0)
	v_add_f32_e32 v32, v24, v25
	v_fmamk_f32 v15, v32, 0xba800000, v15
	v_fmamk_f32 v14, v32, 0xba800000, v14
	v_fmamk_f32 v17, v32, 0xba800000, v17
	v_fmac_f32_e32 v16, 0xba800000, v32
	v_pk_mul_f32 v[24:25], v[16:17], v[16:17]
	v_pk_mul_f32 v[26:27], v[14:15], v[14:15]
	v_fmamk_f32 v11, v32, 0xba800000, v11
	v_pk_mov_b32 v[28:29], v[26:27], v[24:25] op_sel:[1,0]
	v_mov_b32_e32 v27, v25
	v_pk_add_f32 v[24:25], v[28:29], v[26:27]
	v_fmamk_f32 v10, v32, 0xba800000, v10
	v_fmamk_f32 v13, v32, 0xba800000, v13
	v_fmac_f32_e32 v12, 0xba800000, v32
	v_pk_add_f32 v[24:25], v[24:25], v[24:25] op_sel_hi:[0,1]
	v_pk_mul_f32 v[26:27], v[12:13], v[12:13]
	v_pk_mul_f32 v[28:29], v[10:11], v[10:11]
	v_fmamk_f32 v6, v32, 0xba800000, v6
	v_pk_mov_b32 v[30:31], v[28:29], v[26:27] op_sel:[1,0]
	v_mov_b32_e32 v29, v27
	v_fmamk_f32 v7, v32, 0xba800000, v7
	v_fmac_f32_e32 v8, 0xba800000, v32
	v_mul_f32_e32 v24, v6, v6
	v_pk_add_f32 v[26:27], v[30:31], v[28:29]
	v_fmamk_f32 v9, v32, 0xba800000, v9
	v_pk_fma_f32 v[28:29], v[6:7], v[6:7], v[24:25] op_sel_hi:[1,1,0]
	v_mul_f32_e32 v24, v8, v8
	v_pk_add_f32 v[26:27], v[26:27], v[26:27] op_sel_hi:[0,1]
	v_pk_fma_f32 v[30:31], v[8:9], v[8:9], v[24:25] op_sel_hi:[1,1,0]
	v_fmamk_f32 v5, v32, 0xba800000, v5
	v_fmamk_f32 v4, v32, 0xba800000, v4
	v_fmamk_f32 v3, v32, 0xba800000, v3
	v_fmac_f32_e32 v2, 0xba800000, v32
	v_mul_f32_e32 v28, v2, v2
	v_mul_f32_e32 v30, v3, v3
	v_mul_f32_e32 v24, v4, v4
	v_mul_f32_e32 v26, v5, v5
	v_pk_add_f32 v[28:29], v[28:29], v[30:31]
	v_pk_add_f32 v[30:31], v[24:25], v[26:27]
	v_lshl_add_u64 v[44:45], s[0:1], 0, v[172:173]
	v_pk_add_f32 v[28:29], v[28:29], v[30:31]
	v_lshl_add_u64 v[46:47], s[22:23], 0, v[172:173]
	v_add_f32_e32 v40, v28, v29
	ds_bpermute_b32 v41, v33, v40
	s_addc_u32 s19, s19, 0
	flat_load_dwordx4 v[28:31], v[44:45]
	flat_load_dwordx4 v[32:35], v[46:47]
	global_load_dwordx4 v[24:27], v20, s[18:19]
	s_waitcnt lgkmcnt(0)
	v_add_f32_e32 v40, v40, v41
	ds_bpermute_b32 v36, v36, v40
	s_waitcnt lgkmcnt(0)
	v_add_f32_e32 v36, v40, v36
	ds_bpermute_b32 v37, v37, v36
	s_waitcnt lgkmcnt(0)
	v_add_f32_e32 v36, v36, v37
	ds_bpermute_b32 v37, v38, v36
	s_waitcnt lgkmcnt(0)
	v_add_f32_e32 v49, v36, v37
	ds_bpermute_b32 v50, v39, v49
	flat_load_dwordx4 v[36:39], v[44:45] offset:16
	flat_load_dwordx4 v[40:43], v[46:47] offset:16
	s_waitcnt lgkmcnt(0)
	v_add_f32_e32 v49, v49, v50
	ds_bpermute_b32 v48, v48, v49
	s_waitcnt lgkmcnt(0)
	v_add_f32_e32 v48, v49, v48
	v_fmamk_f32 v48, v48, 0x3a800000, v171
	v_mul_f32_e32 v49, 0x4f800000, v48
	v_cmp_gt_f32_e32 vcc, s9, v48
	s_nop 1
	v_cndmask_b32_e32 v48, v48, v49, vcc
	v_sqrt_f32_e32 v49, v48
	s_nop 0
	v_add_u32_e32 v50, -1, v49
	v_fma_f32 v51, -v50, v49, v48
	v_cmp_ge_f32_e64 s[0:1], 0, v51
	v_add_u32_e32 v51, 1, v49
	s_nop 0
	v_cndmask_b32_e64 v50, v49, v50, s[0:1]
	v_fma_f32 v49, -v51, v49, v48
	v_cmp_lt_f32_e64 s[0:1], 0, v49
	s_nop 1
	v_cndmask_b32_e64 v49, v50, v51, s[0:1]
	v_mul_f32_e32 v50, 0x37800000, v49
	v_cndmask_b32_e32 v49, v49, v50, vcc
	v_cmp_class_f32_e32 vcc, v48, v200
	s_nop 1
	v_cndmask_b32_e32 v48, v49, v48, vcc
	v_div_scale_f32 v49, s[0:1], v48, v48, 1.0
	v_rcp_f32_e32 v50, v49
	s_lshl_b64 s[0:1], s[14:15], 11
	v_fma_f32 v51, -v49, v50, 1.0
	v_fmac_f32_e32 v50, v51, v50
	v_div_scale_f32 v51, vcc, 1.0, v48, 1.0
	v_mul_f32_e32 v52, v51, v50
	v_fma_f32 v53, -v49, v52, v51
	v_fmac_f32_e32 v52, v53, v50
	v_fma_f32 v49, -v49, v52, v51
	v_div_fmas_f32 v49, v49, v50, v52
	v_div_fixup_f32 v48, v49, v48, 1.0
	v_pk_mul_f32 v[14:15], v[14:15], v[48:49] op_sel_hi:[1,0]
	v_pk_mul_f32 v[16:17], v[16:17], v[48:49] op_sel_hi:[1,0]
	v_pk_mul_f32 v[10:11], v[10:11], v[48:49] op_sel_hi:[1,0]
	v_pk_mul_f32 v[12:13], v[12:13], v[48:49] op_sel_hi:[1,0]
	s_waitcnt vmcnt(0)
	v_pk_fma_f32 v[14:15], v[28:29], v[14:15], v[32:33]
	v_lshlrev_b32_e32 v52, 16, v26
	v_and_b32_e32 v53, 0xffff0000, v26
	v_mul_f32_e32 v26, 0xbfb8aa3b, v14
	v_exp_f32_e32 v26, v26
	v_mul_f32_e32 v28, 0xbfb8aa3b, v15
	v_exp_f32_e32 v29, v28
	v_pk_fma_f32 v[16:17], v[30:31], v[16:17], v[34:35]
	v_add_f32_e32 v26, 1.0, v26
	v_rcp_f32_e32 v28, v26
	v_add_f32_e32 v26, 1.0, v29
	v_mul_f32_e32 v29, 0xbfb8aa3b, v16
	v_exp_f32_e32 v30, v29
	v_mul_f32_e32 v29, 0xbfb8aa3b, v17
	v_exp_f32_e32 v31, v29
	v_rcp_f32_e32 v29, v26
	v_add_f32_e32 v26, 1.0, v30
	v_rcp_f32_e32 v30, v26
	v_add_f32_e32 v26, 1.0, v31
	v_rcp_f32_e32 v31, v26
	v_pk_mul_f32 v[14:15], v[14:15], v[28:29]
	v_lshlrev_b32_e32 v50, 16, v24
	v_pk_fma_f32 v[10:11], v[36:37], v[10:11], v[40:41]
	v_pk_fma_f32 v[12:13], v[38:39], v[12:13], v[42:43]
	v_pk_mul_f32 v[16:17], v[16:17], v[30:31]
	v_mul_f32_e32 v28, 0xbfb8aa3b, v10
	v_mul_f32_e32 v29, 0xbfb8aa3b, v11
	v_mul_f32_e32 v30, 0xbfb8aa3b, v12
	v_mul_f32_e32 v31, 0xbfb8aa3b, v13
	v_exp_f32_e32 v28, v28
	v_exp_f32_e32 v29, v29
	v_exp_f32_e32 v30, v30
	v_exp_f32_e32 v31, v31
	v_add_f32_e32 v28, 1.0, v28
	v_add_f32_e32 v29, 1.0, v29
	v_add_f32_e32 v30, 1.0, v30
	v_add_f32_e32 v31, 1.0, v31
	v_rcp_f32_e32 v28, v28
	v_rcp_f32_e32 v29, v29
	v_rcp_f32_e32 v30, v30
	v_rcp_f32_e32 v31, v31
	v_and_b32_e32 v51, 0xffff0000, v24
	v_lshlrev_b32_e32 v24, 16, v25
	v_and_b32_e32 v25, 0xffff0000, v25
	v_lshlrev_b32_e32 v26, 16, v27
	v_and_b32_e32 v27, 0xffff0000, v27
	v_pk_mul_f32 v[10:11], v[10:11], v[28:29]
	v_pk_mul_f32 v[12:13], v[12:13], v[30:31]
	v_pk_mul_f32 v[16:17], v[16:17], v[24:25]
	v_pk_mul_f32 v[24:25], v[12:13], v[26:27]
	v_pk_mul_f32 v[12:13], v[10:11], v[52:53]
	v_lshl_add_u64 v[36:37], v[22:23], 0, s[0:1]
	v_pk_mul_f32 v[14:15], v[14:15], v[50:51]
	v_pk_mul_f32 v[6:7], v[6:7], v[48:49] op_sel_hi:[1,0]
	v_cvt_pk_bf16_f32 v10, v14, v15
	v_cvt_pk_bf16_f32 v11, v16, v17
	v_cvt_pk_bf16_f32 v12, v12, v13
	v_cvt_pk_bf16_f32 v13, v24, v25
	global_store_dwordx4 v[36:37], v[10:13], off
	global_load_dwordx4 v[14:17], v21, s[18:19]
	s_nop 0
	flat_load_dwordx4 v[10:13], v[46:47] offset:2048
	flat_load_dwordx4 v[24:27], v[44:45] offset:2048
	flat_load_dwordx4 v[28:31], v[44:45] offset:2064
	flat_load_dwordx4 v[32:35], v[46:47] offset:2064
	v_pk_mul_f32 v[8:9], v[8:9], v[48:49] op_sel_hi:[1,0]
	v_pk_mul_f32 v[2:3], v[2:3], v[48:49] op_sel_hi:[1,0]
	v_pk_mul_f32 v[4:5], v[4:5], v[48:49] op_sel_hi:[1,0]
	s_waitcnt vmcnt(0) lgkmcnt(0)
	v_pk_fma_f32 v[6:7], v[24:25], v[6:7], v[10:11]
	v_pk_fma_f32 v[8:9], v[26:27], v[8:9], v[12:13]
	v_mul_f32_e32 v10, 0xbfb8aa3b, v6
	v_mul_f32_e32 v11, 0xbfb8aa3b, v7
	v_mul_f32_e32 v12, 0xbfb8aa3b, v8
	v_mul_f32_e32 v13, 0xbfb8aa3b, v9
	v_exp_f32_e32 v10, v10
	v_exp_f32_e32 v11, v11
	v_exp_f32_e32 v12, v12
	v_exp_f32_e32 v13, v13
	v_add_f32_e32 v10, 1.0, v10
	v_add_f32_e32 v11, 1.0, v11
	v_add_f32_e32 v12, 1.0, v12
	v_add_f32_e32 v13, 1.0, v13
	v_rcp_f32_e32 v10, v10
	v_rcp_f32_e32 v11, v11
	v_rcp_f32_e32 v12, v12
	v_rcp_f32_e32 v13, v13
	v_pk_fma_f32 v[2:3], v[28:29], v[2:3], v[32:33]
	v_pk_fma_f32 v[4:5], v[30:31], v[4:5], v[34:35]
	v_pk_mul_f32 v[6:7], v[6:7], v[10:11]
	v_pk_mul_f32 v[8:9], v[8:9], v[12:13]
	v_mul_f32_e32 v10, 0xbfb8aa3b, v2
	v_mul_f32_e32 v11, 0xbfb8aa3b, v3
	v_mul_f32_e32 v12, 0xbfb8aa3b, v4
	v_mul_f32_e32 v13, 0xbfb8aa3b, v5
	v_exp_f32_e32 v10, v10
	v_exp_f32_e32 v11, v11
	v_exp_f32_e32 v12, v12
	v_exp_f32_e32 v13, v13
	v_add_f32_e32 v10, 1.0, v10
	v_add_f32_e32 v11, 1.0, v11
	v_add_f32_e32 v12, 1.0, v12
	v_add_f32_e32 v13, 1.0, v13
	v_rcp_f32_e32 v10, v10
	v_rcp_f32_e32 v11, v11
	v_rcp_f32_e32 v12, v12
	v_rcp_f32_e32 v13, v13
	v_lshlrev_b32_e32 v40, 16, v16
	v_and_b32_e32 v41, 0xffff0000, v16
	v_lshlrev_b32_e32 v16, 16, v17
	v_and_b32_e32 v17, 0xffff0000, v17
	v_pk_mul_f32 v[2:3], v[2:3], v[10:11]
	v_pk_mul_f32 v[4:5], v[4:5], v[12:13]
	v_lshlrev_b32_e32 v38, 16, v14
	v_and_b32_e32 v39, 0xffff0000, v14
	v_lshlrev_b32_e32 v14, 16, v15
	v_and_b32_e32 v15, 0xffff0000, v15
	v_pk_mul_f32 v[10:11], v[4:5], v[16:17]
	v_pk_mul_f32 v[4:5], v[2:3], v[40:41]
	v_pk_mul_f32 v[8:9], v[8:9], v[14:15]
	v_pk_mul_f32 v[6:7], v[6:7], v[38:39]
	s_nop 0
	v_cvt_pk_bf16_f32 v2, v6, v7
	v_cvt_pk_bf16_f32 v3, v8, v9
	v_cvt_pk_bf16_f32 v4, v4, v5
	v_cvt_pk_bf16_f32 v5, v10, v11
	global_store_dwordx4 v[36:37], v[2:5], off offset:1024
	s_branch .LBB0_638
